# m22 + LayerNorm panel-seam acquire invalidate issued before the counter spin + DSA select count block without VCC-hazard nops
# speedup vs baseline: 1.0070x; 1.0036x over previous
;     __device__ __forceinline__ bool run(const f32x4 (&v)[2][2][4][2], const Unit& u, int wr, int wc, int fr, int fq, PG8_LAS unsigned char* lds, int wid, int lane) const {
;     ...
;         if (wid == 0) {
;             bool dead = false; const unsigned long long t0 = __builtin_amdgcn_s_memrealtime(); const unsigned want = 8u * (unsigned)ntn;
;             for (;;) {
;                 if ((unsigned)__builtin_amdgcn_readfirstlane(__hip_atomic_load(cnt + 64 * u.pm, __ATOMIC_RELAXED, __HIP_MEMORY_SCOPE_AGENT)) >= want) break;
;                 if (__builtin_amdgcn_s_memrealtime() - t0 > 2000000ull) {
.LBB11_2008:
	s_or_b64 exec, exec, s[14:15]
	s_cmp_gt_u32 s24, 63
	s_cbranch_scc1 .LBB11_2073
	s_memrealtime s[14:15]
	buffer_inv sc1
	s_lshl_b32 s16, s28, 6
	s_ashr_i32 s17, s16, 31
	s_lshl_b64 s[16:17], s[16:17], 2
	s_add_u32 s16, s1, s16
	s_addc_u32 s17, s18, s17
	s_branch .LBB11_2012

;     __device__ __forceinline__ bool run(const f32x4 (&v)[2][2][4][2], const Unit& u, int wr, int wc, int fr, int fq, PG8_LAS unsigned char* lds, int wid, int lane) const {
;     ...
;                 if (__builtin_amdgcn_s_memrealtime() - t0 > 2000000ull) {
;                     if (lane == 0) { unsigned expect = 0u; __hip_atomic_compare_exchange_strong(tmo + 1, &expect, code | (unsigned)(u.pm & 0xff), __ATOMIC_RELAXED, __ATOMIC_RELAXED, __HIP_MEMORY_SCOPE_AGENT);
;                                      __hip_atomic_store(tmo, 1u, __ATOMIC_RELAXED, __HIP_MEMORY_SCOPE_AGENT); }
;                     dead = true; break; }
;                 __builtin_amdgcn_s_sleep(2);
;             }
;             __builtin_amdgcn_fence(__ATOMIC_ACQUIRE, "agent");
.LBB11_2063:
	s_andn2_b64 vcc, exec, s[18:19]
	s_cbranch_vccz .LBB11_2069
	s_waitcnt lgkmcnt(0)
	s_and_saveexec_b64 s[14:15], s[4:5]
	s_xor_b64 s[4:5], exec, s[14:15]
	s_cbranch_execz .LBB11_2066
.LBB11_2066:
	s_or_saveexec_b64 s[14:15], s[4:5]
	s_mov_b64 s[4:5], 0
	s_xor_b64 exec, exec, s[14:15]
	s_cbranch_execz .LBB11_2068
	v_readlane_b32 s1, v252, 16
	s_lshl_b32 s1, s1, 8
	s_and_b32 s4, s28, 0xff
	s_or_b32 s1, s1, s4
	s_addk_i32 s1, 0x700
	v_mov_b32_e32 v2, s1
	global_atomic_cmpswap v3, v[2:3], s[2:3] offset:4
	s_mov_b64 s[4:5], exec
	global_store_dword v3, v209, s[2:3] sc1

;     __device__ __forceinline__ bool run(const f32x4 (&v)[2][2][4][2], const Unit& u, int wr, int wc, int fr, int fq, PG8_LAS unsigned char* lds, int wid, int lane) const {
;     ...
;             __builtin_amdgcn_fence(__ATOMIC_ACQUIRE, "agent");
;             if (lane == 0) flag[0] = dead ? 1u : 0u;
;         }
;         asm volatile("s_waitcnt vmcnt(0) lgkmcnt(0)" ::: "memory"); __builtin_amdgcn_s_barrier(); asm volatile("" ::: "memory");
.LBB11_2070:
	s_waitcnt vmcnt(0)
	s_and_b64 exec, exec, s[6:7]
	v_cndmask_b32_e64 v2, 0, 1, s[2:3]
	ds_write_b32 v3, v2 offset:10240
